# attention unit prologue: first-tile V quads requested together with Q and K (three chained load waits per unit down to one)
# baseline (speedup 1.0000x reference)
; __device__ __forceinline__ void attn_unit(const TI ti, CArgs& a, int b, int hd, int qrow0, int st_lo, int st_hi, float mfix, float lam, float lam_init, const float* subg, unsigned char* ldsg) {
;     ...
;     { const bf16_t* qp = Qb + (size_t)(qrow0 + qt * 32 + r) * 1024 + hd * 128 + c * 64 + 8 * h;
; #pragma unroll
;       for (int ks = 0; ks < 4; ++ks) qf[ks] = *(const bf16x8*)(qp + 16 * ks); }
;     f32x16 O[4];
; #pragma unroll
;     for (int e = 0; e < 4; ++e)
; #pragma unroll
;         for (int i = 0; i < 16; ++i) O[e][i] = 0.f;
;     float lsum = 0.f;
;     u32x4 kreg[2], vreg[2];
;     typedef const __attribute__((address_space(1))) u32x4* gc16_t;
;     const int koff0 = (tid >> 4) * 1024 + (tid & 15) * 8, koff1 = koff0 + 32 * 1024, voff = lane * 1024 + w * 16;
;     ...
;     ATT_LOAD(st_lo); ATT_STORE(0);
;     __syncthreads();
.LBB0_349:
	s_and_b64 vcc, exec, s[4:5]
	s_cbranch_vccz .LBB0_332
	s_ashr_i32 s5, s16, 7
	s_lshl_b32 s4, s5, 11
	s_and_b32 s17, s17, 0x780
	s_or_b32 s17, s4, s17
	v_add_u32_e32 v18, s17, v139
	v_ashrrev_i32_e32 v19, 31, v18
	s_lshl_b32 s17, s16, 4
	s_lshl_b32 s33, s5, 8
	s_ashr_i32 s5, s4, 31
	v_lshlrev_b64 v[18:19], 11, v[18:19]
	s_and_b32 s18, s17, 0x700
	s_lshl_b64 s[34:35], s[4:5], 11
	v_lshl_add_u64 v[18:19], s[46:47], 0, v[18:19]
	s_add_u32 s5, s3, s34
	v_lshl_add_u64 v[152:153], v[18:19], 0, s[18:19]
	s_addc_u32 s17, s6, s35
	v_lshl_add_u64 v[18:19], v[152:153], 0, v[0:1]
	v_mov_b32_e32 v151, v1
	s_add_u32 s5, s5, s18
	v_lshl_add_u64 v[18:19], v[18:19], 0, v[150:151]
	s_addc_u32 s17, s17, 0
	global_load_dwordx4 v[110:113], v[18:19], off
	global_load_dwordx4 v[106:109], v[18:19], off offset:32
	global_load_dwordx4 v[102:105], v[18:19], off offset:64
	global_load_dwordx4 v[98:101], v[18:19], off offset:96
	v_mov_b32_e32 v18, s5
	v_mov_b32_e32 v19, s17
	v_lshl_add_u64 v[22:23], v[140:141], 1, v[18:19]
	global_load_dwordx4 v[18:21], v[22:23], off
	v_add_co_u32_e32 v22, vcc, s79, v22
	s_add_u32 s5, s7, s34
	s_nop 0
	v_addc_co_u32_e32 v23, vcc, 0, v23, vcc
	global_load_dwordx4 v[22:25], v[22:23], off
	s_addc_u32 s17, s10, s35
	s_add_u32 s5, s5, s18
	s_addc_u32 s17, s17, 0
	v_mov_b32_e32 v26, s5
	v_mov_b32_e32 v27, s17
	v_lshl_add_u64 v[26:27], v[142:143], 1, v[26:27]
	global_load_dwordx4 v[230:233], v[26:27], off
	global_load_dwordx4 v[234:237], v[26:27], off offset:16
	s_add_u32 s27, s3, s18
	s_addc_u32 s34, s6, 0
	s_add_u32 s18, s7, s18
	v_mov_b32_e32 v0, 0
	s_mov_b32 s17, 0
	s_addc_u32 s35, s10, 0
	s_add_i32 s37, s33, 0x3840
	s_or_b32 s39, s4, 64
	v_mov_b32_e32 v28, v0
	v_mov_b32_e32 v29, v0
	v_mov_b32_e32 v30, v0
	v_mov_b32_e32 v31, v0
	v_mov_b32_e32 v32, v0
	v_mov_b32_e32 v33, v0
	v_mov_b32_e32 v34, 0
	v_mov_b32_e32 v35, v0
	v_mov_b32_e32 v36, v0
	v_mov_b32_e32 v37, v0
	v_mov_b32_e32 v38, v0
	v_mov_b32_e32 v39, v0
	v_mov_b32_e32 v40, v0
	v_mov_b32_e32 v41, v0
	v_mov_b32_e32 v42, v0
	v_mov_b32_e32 v43, v0
	v_mov_b32_e32 v44, v0
	v_mov_b32_e32 v45, v0
	v_mov_b32_e32 v46, v0
	v_mov_b32_e32 v47, v0
	v_mov_b32_e32 v48, v0
	v_mov_b32_e32 v49, v0
	v_mov_b32_e32 v66, 0
	v_mov_b32_e32 v67, v0
	v_mov_b32_e32 v68, v0
	v_mov_b32_e32 v69, v0
	v_mov_b32_e32 v70, v0
	v_mov_b32_e32 v71, v0
	v_mov_b32_e32 v72, v0
	v_mov_b32_e32 v73, v0
	v_mov_b32_e32 v74, v0
	v_mov_b32_e32 v75, v0
	v_mov_b32_e32 v76, v0
	v_mov_b32_e32 v77, v0
	v_mov_b32_e32 v78, v0
	v_mov_b32_e32 v79, v0
	v_mov_b32_e32 v80, v0
	v_mov_b32_e32 v81, v0
	v_mov_b32_e32 v50, 0
	v_mov_b32_e32 v51, v0
	v_mov_b32_e32 v52, v0
	v_mov_b32_e32 v53, v0
	v_mov_b32_e32 v54, v0
	v_mov_b32_e32 v55, v0
	v_mov_b32_e32 v56, v0
	v_mov_b32_e32 v57, v0
	v_mov_b32_e32 v58, v0
	s_waitcnt vmcnt(3)
	ds_write_b128 v169, v[18:21]
	s_waitcnt vmcnt(2)
	ds_write_b128 v170, v[22:25]
	v_mov_b32_e32 v59, v0
	v_mov_b32_e32 v60, v0
	v_mov_b32_e32 v61, v0
	v_mov_b32_e32 v62, v0
	v_mov_b32_e32 v63, v0
	v_mov_b32_e32 v64, v0
	v_mov_b32_e32 v65, v0
	s_waitcnt vmcnt(1)
	ds_write_b16 v159, v230 offset:17408
	ds_write_b16_d16_hi v159, v230 offset:17552
	v_mov_b32_e32 v18, 0
	v_mov_b32_e32 v26, v0
	v_mov_b32_e32 v27, v0
	s_waitcnt vmcnt(0)
	ds_write_b16 v159, v234 offset:18560
	ds_write_b16_d16_hi v159, v234 offset:18704
	ds_write_b16 v159, v231 offset:17696
	ds_write_b16_d16_hi v159, v231 offset:17840
	ds_write_b16 v159, v235 offset:18848
	ds_write_b16_d16_hi v159, v235 offset:18992
	ds_write_b16 v159, v232 offset:17984
	ds_write_b16_d16_hi v159, v232 offset:18128
	ds_write_b16 v159, v236 offset:19136
	ds_write_b16_d16_hi v159, v236 offset:19280
	ds_write_b16 v159, v233 offset:18272
	ds_write_b16_d16_hi v159, v233 offset:18416
	ds_write_b16 v159, v237 offset:19424
	ds_write_b16_d16_hi v159, v237 offset:19568
	v_mov_b32_e32 v19, v0
	v_mov_b32_e32 v20, v0
	v_mov_b32_e32 v21, v0
	v_mov_b32_e32 v22, v0
	v_mov_b32_e32 v23, v0
	v_mov_b32_e32 v24, v0
	v_mov_b32_e32 v25, v0
	s_waitcnt lgkmcnt(0)
	s_barrier
	s_branch .LBB0_352
